# ADIFF fast loop: DMA address math for chunk ch+3 moved from right after the per-chunk barrier to the first DMA piece (one MFMA pair later, inside an MFMA shadow)
# baseline (speedup 1.0000x reference)
; #define LAS __attribute__((address_space(3)))
; __device__ __forceinline__ void diff_attn_phase(const Params& p, LAS unsigned char* lds) {
;     ...
;         auto issue = [&](int ch, int stg) {
;             const char* kg = (const char*)(kp + (tokb + 64 * ch) * ld); const char* vg = (const char*)(vp + (tokb + 64 * ch) * ld);
;             LAS unsigned char* sb = lds + stg * STG;
; #pragma unroll
;             for (int i = 0; i < 2; ++i) { unsigned o = doff[i]; asm volatile("" : "+v"(o));
;                 __builtin_amdgcn_global_load_lds((const void*)(kg + o), (LAS void*)(sb + dlds[i]), 16, 0, 0);
;                 __builtin_amdgcn_global_load_lds((const void*)(vg + o), (LAS void*)(sb + 16384 + dlds[i]), 16, 0, 0); }
;         };
;         issue(0, 0); issue(1, 1);
;         int s_cur = 0, s_nn = 2;
;         for (int ch = 0; ch < NCH; ++ch) {
;             if (ch + 1 < NCH) asm volatile("s_waitcnt vmcnt(4)" ::: "memory"); else asm volatile("s_waitcnt vmcnt(0)" ::: "memory");
;             __builtin_amdgcn_s_barrier(); asm volatile("" ::: "memory");
;             if (ch + 2 < NCH) issue(ch + 2, s_nn);
;             const LAS unsigned char* Ksb = lds + s_cur * STG; const LAS unsigned char* Vsb = Ksb + 16384;
;             s_nn = s_cur; s_cur = (s_cur == 2) ? 0 : s_cur + 1;
;     ...
;                 for (int t = 0; t < 4; ++t) {
;                     const LAS unsigned char* a0 = Vu + (vb0l ^ (64 * t)); const LAS unsigned char* a1 = Vu + (vb1l ^ (64 * t));
;                     const bf16x8 v0 = tr_pair(a0, a1), v1 = tr_pair(a0 + 4096, a1 + 4096);
;                     O[0][t] = __builtin_amdgcn_mfma_f32_32x32x16_bf16(v0, P[0][0], O[0][t], 0, 0, 0);
;                     O[1][t] = __builtin_amdgcn_mfma_f32_32x32x16_bf16(v0, P[1][0], O[1][t], 0, 0, 0);
.Lfb_w1F:
	s_barrier
	s_add_i32 s2, s29, 1
	s_and_b32 s2, s2, 3
	s_mov_b32 s37, 0x8000
	s_cmp_eq_u32 s2, 0
	s_cselect_b32 s37, 0xfffe8000, s37
	v_add_u32_e32 v1, s37, v1
	s_waitcnt lgkmcnt(6)
	v_mfma_f32_32x32x16_bf16 v[114:129], v[198:201], v[222:225], v[114:129]
	v_exp_f32_e32 v130, v130
	v_exp_f32_e32 v131, v131
	v_mfma_f32_32x32x16_bf16 v[50:65], v[198:201], v[226:229], v[50:65]
	v_add_u32_e32 v198, v246, v1
	ds_read_b128 v[198:201], v198
	v_exp_f32_e32 v132, v132
	v_exp_f32_e32 v133, v133
	s_cmpk_gt_u32 s29, 0x7c
	s_cbranch_scc1 .Lfb_nd0F
	s_add_i32 s2, s29, 3
	s_lshl_b32 s10, s2, 6
	s_add_u32 s10, s26, s10
	s_addc_u32 s11, s27, 0
	s_lshl_b64 s[10:11], s[10:11], 13
	s_add_u32 s42, s25, s10
	s_addc_u32 s43, s28, s11
	s_add_u32 s10, s22, s10
	s_addc_u32 s11, s23, s11
	s_and_b32 s2, s2, 3
	s_lshl_b32 s2, s2, 15
	s_add_i32 s2, s2, s34
	s_mov_b32 m0, s2
	s_nop 0
	global_load_lds_dwordx4 v241, s[42:43]
